# rw_scan step loop hand-rewritten: 2 rows x 4 keys per thread, packed f32 math, LDS operand reads halved
# speedup vs baseline: 1.0286x; 1.0286x over previous
; #define RW_GLOAD(ck) do { const int row_ = seq_row(b, dir, (ck) * 64 + tok); gr = *(const u32x4*)(R + (size_t)row_ * D + ch0); gk = *(const u32x4*)(Kx + (size_t)row_ * D + ch0); gv = *(const u32x4*)(Vx + (size_t)row_ * D + ch0); \
;         gw = *(const u32x4*)(W + ((size_t)row_ * 2 + dir) * D + ch0); ga = *(const u32x4*)(AD + ((size_t)row_ * 2 + dir) * D + ch0); } while (0)
; __device__ __forceinline__ void phase_rw_scan(KP P, const Ctx& c) {
;     ...
;         const int b = chain >> 6, hd = (chain >> 1) & 31, dir = chain & 1;
;         bf16_t* Y = (bf16_t*)(P->ws + (dir ? L_Y1 : L_Y0));
;         const int ch0 = hd * 64 + cq * 8;
;         float kkw[8], kaw[8];
; #pragma unroll
;         for (int j = 0; j < 8; ++j) { kkw[j] = P->in[I_RWKK][ch0 + j]; kaw[j] = P->in[I_RWKA][ch0 + j]; }
;         float s[8] = {0.f, 0.f, 0.f, 0.f, 0.f, 0.f, 0.f, 0.f};
;         u32x4 gr, gk, gv, gw, ga;
;     ...
;         RW_GLOAD(0);
.LBB0_1753:
	s_or_b64 exec, exec, s[48:49]
	s_waitcnt vmcnt(7)
	v_ashrrev_i32_e32 v27, 31, v26
	v_lshlrev_b64 v[28:29], 12, v[26:27]
	s_waitcnt vmcnt(5)
	v_lshlrev_b64 v[34:35], 13, v[26:27]
	v_lshl_add_u64 v[20:21], s[40:41], 0, v[28:29]
	v_lshlrev_b32_e32 v118, 1, v18
	v_lshl_or_b32 v34, s5, 12, v34
	v_lshl_add_u64 v[18:19], v[20:21], 0, v[118:119]
	v_lshl_add_u64 v[20:21], s[42:43], 0, v[28:29]
	v_lshl_add_u64 v[28:29], s[50:51], 0, v[28:29]
	v_lshl_add_u64 v[26:27], s[56:57], 0, v[34:35]
	v_lshl_add_u64 v[34:35], s[58:59], 0, v[34:35]
	v_lshl_add_u64 v[22:23], v[20:21], 0, v[118:119]
	v_lshl_add_u64 v[28:29], v[28:29], 0, v[118:119]
	v_lshl_add_u64 v[30:31], v[26:27], 0, v[118:119]
	v_lshl_add_u64 v[34:35], v[34:35], 0, v[118:119]
	global_load_dwordx4 v[18:21], v[18:19], off
	s_nop 0
	global_load_dwordx4 v[22:25], v[22:23], off
	s_nop 0
	global_load_dwordx4 v[26:29], v[28:29], off
	s_nop 0
	global_load_dwordx4 v[30:33], v[30:31], off
	s_and_b64 s[8:9], s[46:47], exec
	global_load_dwordx4 v[34:37], v[34:35], off
	s_mov_b32 s8, 0x3cc00000
	s_cselect_b32 s9, s8, 0x45400000
	s_add_u32 s10, s38, s9
	s_waitcnt vmcnt(7)
	v_mov_b32_e32 v38, v6
	v_mov_b32_e32 v6, v8
	s_addc_u32 s11, s39, 0
	s_mov_b32 s8, 0
	s_lshl_b32 s5, s5, 11
	v_lshl_add_u64 v[122:123], s[40:41], 0, v[118:119]
	v_lshl_add_u64 v[124:125], s[42:43], 0, v[118:119]
	v_lshl_add_u64 v[126:127], s[50:51], 0, v[118:119]
	v_lshl_add_u64 v[128:129], s[56:57], 0, v[118:119]
	v_lshl_add_u64 v[130:131], s[58:59], 0, v[118:119]
	v_lshl_add_u64 v[132:133], s[10:11], 0, v[118:119]
	v_swap_b32 v8, v5
	v_mov_b32_e32 v6, v3
	v_mov_b32_e32 v3, v38
	v_mov_b32_e32 v118, 0
	v_mov_b32_e32 v161, 0
	v_mov_b32_e32 v162, 0
	v_mov_b32_e32 v163, 0
	v_mov_b32_e32 v164, 0
	v_mov_b32_e32 v165, 0
	v_mov_b32_e32 v166, 0
	v_mov_b32_e32 v167, 0
	v_mov_b32_e32 v170, 0
	v_mov_b32_e32 v171, 0
	v_mov_b32_e32 v172, 0
	v_mov_b32_e32 v173, 0
	v_mov_b32_e32 v174, 0
	v_mov_b32_e32 v175, 0
	v_mov_b32_e32 v176, 0
	v_mov_b32_e32 v177, 0
	s_branch .LBB0_1755

; __device__ __forceinline__ void phase_rw_scan(KP P, const Ctx& c) {
;     ...
;             RW_LLOAD(A, 0);
; #pragma unroll 1
;             for (int tk = 0; tk < 64; tk += 2) {
;                 RW_LLOAD(B, tk + 1);
;                 RW_STEP(A, tk);
;                 RW_LLOAD(A, (tk + 2) & 63);
;                 RW_STEP(B, tk + 1);
;             }
.LBB0_1759:
	v_and_b32_e32 v240, 15, v0
	v_lshrrev_b32_e32 v242, 4, v0
	v_cmp_eq_u32_e64 s[60:61], 0, v240
	v_lshlrev_b32_e32 v240, 4, v240
	v_lshlrev_b32_e32 v242, 3, v242
	v_add_u32_e32 v241, 0x10000, v240
	v_add_u32_e32 v242, 0x14000, v242
	v_mov_b32_e32 v243, 0x1c000
	s_mov_b32 s62, 0
	ds_read_b128 v[178:181], v240 offset:32768
	ds_read_b128 v[182:185], v240
	ds_read_b128 v[186:189], v240 offset:16384
	ds_read_b128 v[190:193], v241
	ds_read_b64 v[198:199], v242
	ds_read_b128 v[194:197], v240 offset:49152
	ds_read_b64 v[200:201], v243
	ds_read_b32 v245, v243
.Lrw_loop:
	s_waitcnt lgkmcnt(6)
	v_pk_mul_f32 v[226:227], v[170:171], v[178:179] op_sel_hi:[1,0]
	v_pk_mul_f32 v[228:229], v[170:171], v[182:183] op_sel_hi:[1,0]
	v_pk_fma_f32 v[226:227], v[172:173], v[178:179], v[226:227] op_sel:[0,1,0]
	v_pk_fma_f32 v[228:229], v[172:173], v[182:183], v[228:229] op_sel:[0,1,0]
	v_pk_fma_f32 v[226:227], v[174:175], v[180:181], v[226:227] op_sel_hi:[1,0,1]
	v_pk_fma_f32 v[228:229], v[174:175], v[184:185], v[228:229] op_sel_hi:[1,0,1]
	v_pk_fma_f32 v[226:227], v[176:177], v[180:181], v[226:227] op_sel:[0,1,0]
	v_pk_fma_f32 v[228:229], v[176:177], v[184:185], v[228:229] op_sel:[0,1,0]
	ds_read_b128 v[202:205], v240 offset:33024
	ds_read_b128 v[206:209], v240 offset:256
	s_waitcnt lgkmcnt(5)
	v_pk_mul_f32 v[230:231], v[170:171], v[186:187] op_sel_hi:[1,0]
	v_pk_mul_f32 v[232:233], v[172:173], v[186:187] op_sel:[0,1]
	v_pk_mul_f32 v[234:235], v[174:175], v[188:189] op_sel_hi:[1,0]
	v_pk_mul_f32 v[236:237], v[176:177], v[188:189] op_sel:[0,1]
	v_pk_fma_f32 v[230:231], v[198:199], v[190:191], v[230:231] op_sel_hi:[1,0,1]
	v_pk_fma_f32 v[232:233], v[198:199], v[190:191], v[232:233] op_sel:[0,1,0]
	v_pk_fma_f32 v[234:235], v[198:199], v[192:193], v[234:235] op_sel_hi:[1,0,1]
	v_pk_fma_f32 v[236:237], v[198:199], v[192:193], v[236:237] op_sel:[0,1,0]
	ds_read_b128 v[210:213], v240 offset:16640
	ds_read_b128 v[214:217], v241 offset:256
	ds_read_b64 v[222:223], v242 offset:256
	v_add_f32_dpp v226, v226, v226 quad_perm:[1,0,3,2] row_mask:0xf bank_mask:0xf
	v_add_f32_dpp v227, v227, v227 quad_perm:[1,0,3,2] row_mask:0xf bank_mask:0xf
	v_add_f32_dpp v228, v228, v228 quad_perm:[1,0,3,2] row_mask:0xf bank_mask:0xf
	v_add_f32_dpp v229, v229, v229 quad_perm:[1,0,3,2] row_mask:0xf bank_mask:0xf
	v_add_f32_dpp v226, v226, v226 quad_perm:[2,3,0,1] row_mask:0xf bank_mask:0xf
	v_add_f32_dpp v227, v227, v227 quad_perm:[2,3,0,1] row_mask:0xf bank_mask:0xf
	v_add_f32_dpp v228, v228, v228 quad_perm:[2,3,0,1] row_mask:0xf bank_mask:0xf
	v_add_f32_dpp v229, v229, v229 quad_perm:[2,3,0,1] row_mask:0xf bank_mask:0xf
	v_add_f32_dpp v226, v226, v226 row_half_mirror row_mask:0xf bank_mask:0xf
	v_add_f32_dpp v227, v227, v227 row_half_mirror row_mask:0xf bank_mask:0xf
	v_add_f32_dpp v228, v228, v228 row_half_mirror row_mask:0xf bank_mask:0xf
	v_add_f32_dpp v229, v229, v229 row_half_mirror row_mask:0xf bank_mask:0xf
	v_add_f32_dpp v226, v226, v226 row_mirror row_mask:0xf bank_mask:0xf
	v_add_f32_dpp v227, v227, v227 row_mirror row_mask:0xf bank_mask:0xf
	v_add_f32_dpp v228, v228, v228 row_mirror row_mask:0xf bank_mask:0xf
	v_add_f32_dpp v229, v229, v229 row_mirror row_mask:0xf bank_mask:0xf
	s_waitcnt lgkmcnt(6)
	v_pk_fma_f32 v[170:171], v[226:227], v[194:195], v[230:231] op_sel_hi:[1,0,1] neg_lo:[1,0,0] neg_hi:[1,0,0]
	v_pk_fma_f32 v[172:173], v[226:227], v[194:195], v[232:233] op_sel:[0,1,0] neg_lo:[1,0,0] neg_hi:[1,0,0]
	v_pk_fma_f32 v[174:175], v[226:227], v[196:197], v[234:235] op_sel_hi:[1,0,1] neg_lo:[1,0,0] neg_hi:[1,0,0]
	v_pk_fma_f32 v[176:177], v[226:227], v[196:197], v[236:237] op_sel:[0,1,0] neg_lo:[1,0,0] neg_hi:[1,0,0]
	v_pk_fma_f32 v[246:247], v[226:227], v[200:201], v[228:229] op_sel_hi:[1,0,1] neg_lo:[1,0,0] neg_hi:[1,0,0]
	v_pk_fma_f32 v[246:247], v[198:199], v[200:201], v[246:247] op_sel:[0,1,0]
	ds_read_b128 v[218:221], v240 offset:49408
	ds_read_b64 v[224:225], v243 offset:8
	s_mov_b64 exec, s[60:61]
	ds_write_b64 v242, v[246:247] offset:16384
	s_mov_b64 exec, -1
	s_waitcnt lgkmcnt(6)
	v_pk_mul_f32 v[226:227], v[170:171], v[202:203] op_sel_hi:[1,0]
	v_pk_mul_f32 v[228:229], v[170:171], v[206:207] op_sel_hi:[1,0]
	v_pk_fma_f32 v[226:227], v[172:173], v[202:203], v[226:227] op_sel:[0,1,0]
	v_pk_fma_f32 v[228:229], v[172:173], v[206:207], v[228:229] op_sel:[0,1,0]
	v_pk_fma_f32 v[226:227], v[174:175], v[204:205], v[226:227] op_sel_hi:[1,0,1]
	v_pk_fma_f32 v[228:229], v[174:175], v[208:209], v[228:229] op_sel_hi:[1,0,1]
	v_pk_fma_f32 v[226:227], v[176:177], v[204:205], v[226:227] op_sel:[0,1,0]
	v_pk_fma_f32 v[228:229], v[176:177], v[208:209], v[228:229] op_sel:[0,1,0]
	ds_read_b128 v[178:181], v240 offset:33280
	ds_read_b128 v[182:185], v240 offset:512
	s_waitcnt lgkmcnt(5)
; __device__ __forceinline__ void phase_rw_scan(KP P, const Ctx& c) {
;     ...
;             RW_LLOAD(A, 0);
; #pragma unroll 1
;             for (int tk = 0; tk < 64; tk += 2) {
;                 RW_LLOAD(B, tk + 1);
;                 RW_STEP(A, tk);
;                 RW_LLOAD(A, (tk + 2) & 63);
;                 RW_STEP(B, tk + 1);
;             }
	v_pk_mul_f32 v[230:231], v[170:171], v[210:211] op_sel_hi:[1,0]
	v_pk_mul_f32 v[232:233], v[172:173], v[210:211] op_sel:[0,1]
	v_pk_mul_f32 v[234:235], v[174:175], v[212:213] op_sel_hi:[1,0]
	v_pk_mul_f32 v[236:237], v[176:177], v[212:213] op_sel:[0,1]
	v_pk_fma_f32 v[230:231], v[222:223], v[214:215], v[230:231] op_sel_hi:[1,0,1]
	v_pk_fma_f32 v[232:233], v[222:223], v[214:215], v[232:233] op_sel:[0,1,0]
	v_pk_fma_f32 v[234:235], v[222:223], v[216:217], v[234:235] op_sel_hi:[1,0,1]
	v_pk_fma_f32 v[236:237], v[222:223], v[216:217], v[236:237] op_sel:[0,1,0]
	ds_read_b128 v[186:189], v240 offset:16896
	ds_read_b128 v[190:193], v241 offset:512
	ds_read_b64 v[198:199], v242 offset:512
	v_add_f32_dpp v226, v226, v226 quad_perm:[1,0,3,2] row_mask:0xf bank_mask:0xf
	v_add_f32_dpp v227, v227, v227 quad_perm:[1,0,3,2] row_mask:0xf bank_mask:0xf
	v_add_f32_dpp v228, v228, v228 quad_perm:[1,0,3,2] row_mask:0xf bank_mask:0xf
	v_add_f32_dpp v229, v229, v229 quad_perm:[1,0,3,2] row_mask:0xf bank_mask:0xf
	v_add_f32_dpp v226, v226, v226 quad_perm:[2,3,0,1] row_mask:0xf bank_mask:0xf
	v_add_f32_dpp v227, v227, v227 quad_perm:[2,3,0,1] row_mask:0xf bank_mask:0xf
	v_add_f32_dpp v228, v228, v228 quad_perm:[2,3,0,1] row_mask:0xf bank_mask:0xf
	v_add_f32_dpp v229, v229, v229 quad_perm:[2,3,0,1] row_mask:0xf bank_mask:0xf
	v_add_f32_dpp v226, v226, v226 row_half_mirror row_mask:0xf bank_mask:0xf
	v_add_f32_dpp v227, v227, v227 row_half_mirror row_mask:0xf bank_mask:0xf
	v_add_f32_dpp v228, v228, v228 row_half_mirror row_mask:0xf bank_mask:0xf
	v_add_f32_dpp v229, v229, v229 row_half_mirror row_mask:0xf bank_mask:0xf
	v_add_f32_dpp v226, v226, v226 row_mirror row_mask:0xf bank_mask:0xf
	v_add_f32_dpp v227, v227, v227 row_mirror row_mask:0xf bank_mask:0xf
	v_add_f32_dpp v228, v228, v228 row_mirror row_mask:0xf bank_mask:0xf
	v_add_f32_dpp v229, v229, v229 row_mirror row_mask:0xf bank_mask:0xf
	s_waitcnt lgkmcnt(6)
	v_pk_fma_f32 v[170:171], v[226:227], v[218:219], v[230:231] op_sel_hi:[1,0,1] neg_lo:[1,0,0] neg_hi:[1,0,0]
	v_pk_fma_f32 v[172:173], v[226:227], v[218:219], v[232:233] op_sel:[0,1,0] neg_lo:[1,0,0] neg_hi:[1,0,0]
	v_pk_fma_f32 v[174:175], v[226:227], v[220:221], v[234:235] op_sel_hi:[1,0,1] neg_lo:[1,0,0] neg_hi:[1,0,0]
	v_pk_fma_f32 v[176:177], v[226:227], v[220:221], v[236:237] op_sel:[0,1,0] neg_lo:[1,0,0] neg_hi:[1,0,0]
	v_pk_fma_f32 v[246:247], v[226:227], v[224:225], v[228:229] op_sel_hi:[1,0,1] neg_lo:[1,0,0] neg_hi:[1,0,0]
	v_pk_fma_f32 v[246:247], v[222:223], v[224:225], v[246:247] op_sel:[0,1,0]
	ds_read_b128 v[194:197], v240 offset:49664
	ds_read_b64 v[200:201], v243 offset:16
	s_mov_b64 exec, s[60:61]
	ds_write_b64 v242, v[246:247] offset:16640
	s_mov_b64 exec, -1
	s_waitcnt lgkmcnt(6)
	v_pk_mul_f32 v[226:227], v[170:171], v[178:179] op_sel_hi:[1,0]
	v_pk_mul_f32 v[228:229], v[170:171], v[182:183] op_sel_hi:[1,0]
	v_pk_fma_f32 v[226:227], v[172:173], v[178:179], v[226:227] op_sel:[0,1,0]
	v_pk_fma_f32 v[228:229], v[172:173], v[182:183], v[228:229] op_sel:[0,1,0]
	v_pk_fma_f32 v[226:227], v[174:175], v[180:181], v[226:227] op_sel_hi:[1,0,1]
	v_pk_fma_f32 v[228:229], v[174:175], v[184:185], v[228:229] op_sel_hi:[1,0,1]
	v_pk_fma_f32 v[226:227], v[176:177], v[180:181], v[226:227] op_sel:[0,1,0]
	v_pk_fma_f32 v[228:229], v[176:177], v[184:185], v[228:229] op_sel:[0,1,0]
	ds_read_b128 v[202:205], v240 offset:33536
	ds_read_b128 v[206:209], v240 offset:768
	s_waitcnt lgkmcnt(5)
	v_pk_mul_f32 v[230:231], v[170:171], v[186:187] op_sel_hi:[1,0]
	v_pk_mul_f32 v[232:233], v[172:173], v[186:187] op_sel:[0,1]
	v_pk_mul_f32 v[234:235], v[174:175], v[188:189] op_sel_hi:[1,0]
	v_pk_mul_f32 v[236:237], v[176:177], v[188:189] op_sel:[0,1]
	v_pk_fma_f32 v[230:231], v[198:199], v[190:191], v[230:231] op_sel_hi:[1,0,1]
	v_pk_fma_f32 v[232:233], v[198:199], v[190:191], v[232:233] op_sel:[0,1,0]
	v_pk_fma_f32 v[234:235], v[198:199], v[192:193], v[234:235] op_sel_hi:[1,0,1]
	v_pk_fma_f32 v[236:237], v[198:199], v[192:193], v[236:237] op_sel:[0,1,0]
	ds_read_b128 v[210:213], v240 offset:17152
	ds_read_b128 v[214:217], v241 offset:768
	ds_read_b64 v[222:223], v242 offset:768
	v_add_f32_dpp v226, v226, v226 quad_perm:[1,0,3,2] row_mask:0xf bank_mask:0xf
	v_add_f32_dpp v227, v227, v227 quad_perm:[1,0,3,2] row_mask:0xf bank_mask:0xf
	v_add_f32_dpp v228, v228, v228 quad_perm:[1,0,3,2] row_mask:0xf bank_mask:0xf
	v_add_f32_dpp v229, v229, v229 quad_perm:[1,0,3,2] row_mask:0xf bank_mask:0xf
	v_add_f32_dpp v226, v226, v226 quad_perm:[2,3,0,1] row_mask:0xf bank_mask:0xf
	v_add_f32_dpp v227, v227, v227 quad_perm:[2,3,0,1] row_mask:0xf bank_mask:0xf
	v_add_f32_dpp v228, v228, v228 quad_perm:[2,3,0,1] row_mask:0xf bank_mask:0xf
	v_add_f32_dpp v229, v229, v229 quad_perm:[2,3,0,1] row_mask:0xf bank_mask:0xf
	v_add_f32_dpp v226, v226, v226 row_half_mirror row_mask:0xf bank_mask:0xf
	v_add_f32_dpp v227, v227, v227 row_half_mirror row_mask:0xf bank_mask:0xf
	v_add_f32_dpp v228, v228, v228 row_half_mirror row_mask:0xf bank_mask:0xf
	v_add_f32_dpp v229, v229, v229 row_half_mirror row_mask:0xf bank_mask:0xf
	v_add_f32_dpp v226, v226, v226 row_mirror row_mask:0xf bank_mask:0xf
	v_add_f32_dpp v227, v227, v227 row_mirror row_mask:0xf bank_mask:0xf
	v_add_f32_dpp v228, v228, v228 row_mirror row_mask:0xf bank_mask:0xf
	v_add_f32_dpp v229, v229, v229 row_mirror row_mask:0xf bank_mask:0xf
	s_waitcnt lgkmcnt(6)
; __device__ __forceinline__ void phase_rw_scan(KP P, const Ctx& c) {
;     ...
;             RW_LLOAD(A, 0);
; #pragma unroll 1
;             for (int tk = 0; tk < 64; tk += 2) {
;                 RW_LLOAD(B, tk + 1);
;                 RW_STEP(A, tk);
;                 RW_LLOAD(A, (tk + 2) & 63);
;                 RW_STEP(B, tk + 1);
;             }
	v_pk_fma_f32 v[170:171], v[226:227], v[194:195], v[230:231] op_sel_hi:[1,0,1] neg_lo:[1,0,0] neg_hi:[1,0,0]
	v_pk_fma_f32 v[172:173], v[226:227], v[194:195], v[232:233] op_sel:[0,1,0] neg_lo:[1,0,0] neg_hi:[1,0,0]
	v_pk_fma_f32 v[174:175], v[226:227], v[196:197], v[234:235] op_sel_hi:[1,0,1] neg_lo:[1,0,0] neg_hi:[1,0,0]
	v_pk_fma_f32 v[176:177], v[226:227], v[196:197], v[236:237] op_sel:[0,1,0] neg_lo:[1,0,0] neg_hi:[1,0,0]
	v_pk_fma_f32 v[246:247], v[226:227], v[200:201], v[228:229] op_sel_hi:[1,0,1] neg_lo:[1,0,0] neg_hi:[1,0,0]
	v_pk_fma_f32 v[246:247], v[198:199], v[200:201], v[246:247] op_sel:[0,1,0]
	ds_read_b128 v[218:221], v240 offset:49920
	ds_read_b64 v[224:225], v243 offset:24
	s_mov_b64 exec, s[60:61]
	ds_write_b64 v242, v[246:247] offset:16896
	s_mov_b64 exec, -1
	s_waitcnt lgkmcnt(6)
	v_pk_mul_f32 v[226:227], v[170:171], v[202:203] op_sel_hi:[1,0]
	v_pk_mul_f32 v[228:229], v[170:171], v[206:207] op_sel_hi:[1,0]
	v_pk_fma_f32 v[226:227], v[172:173], v[202:203], v[226:227] op_sel:[0,1,0]
	v_pk_fma_f32 v[228:229], v[172:173], v[206:207], v[228:229] op_sel:[0,1,0]
	v_pk_fma_f32 v[226:227], v[174:175], v[204:205], v[226:227] op_sel_hi:[1,0,1]
	v_pk_fma_f32 v[228:229], v[174:175], v[208:209], v[228:229] op_sel_hi:[1,0,1]
	v_pk_fma_f32 v[226:227], v[176:177], v[204:205], v[226:227] op_sel:[0,1,0]
	v_pk_fma_f32 v[228:229], v[176:177], v[208:209], v[228:229] op_sel:[0,1,0]
	ds_read_b128 v[178:181], v240 offset:33792
	ds_read_b128 v[182:185], v240 offset:1024
	s_waitcnt lgkmcnt(5)
	v_pk_mul_f32 v[230:231], v[170:171], v[210:211] op_sel_hi:[1,0]
	v_pk_mul_f32 v[232:233], v[172:173], v[210:211] op_sel:[0,1]
	v_pk_mul_f32 v[234:235], v[174:175], v[212:213] op_sel_hi:[1,0]
	v_pk_mul_f32 v[236:237], v[176:177], v[212:213] op_sel:[0,1]
	v_pk_fma_f32 v[230:231], v[222:223], v[214:215], v[230:231] op_sel_hi:[1,0,1]
	v_pk_fma_f32 v[232:233], v[222:223], v[214:215], v[232:233] op_sel:[0,1,0]
	v_pk_fma_f32 v[234:235], v[222:223], v[216:217], v[234:235] op_sel_hi:[1,0,1]
	v_pk_fma_f32 v[236:237], v[222:223], v[216:217], v[236:237] op_sel:[0,1,0]
	ds_read_b128 v[186:189], v240 offset:17408
	ds_read_b128 v[190:193], v241 offset:1024
	ds_read_b64 v[198:199], v242 offset:1024
	v_add_f32_dpp v226, v226, v226 quad_perm:[1,0,3,2] row_mask:0xf bank_mask:0xf
	v_add_f32_dpp v227, v227, v227 quad_perm:[1,0,3,2] row_mask:0xf bank_mask:0xf
	v_add_f32_dpp v228, v228, v228 quad_perm:[1,0,3,2] row_mask:0xf bank_mask:0xf
	v_add_f32_dpp v229, v229, v229 quad_perm:[1,0,3,2] row_mask:0xf bank_mask:0xf
	v_add_f32_dpp v226, v226, v226 quad_perm:[2,3,0,1] row_mask:0xf bank_mask:0xf
	v_add_f32_dpp v227, v227, v227 quad_perm:[2,3,0,1] row_mask:0xf bank_mask:0xf
	v_add_f32_dpp v228, v228, v228 quad_perm:[2,3,0,1] row_mask:0xf bank_mask:0xf
	v_add_f32_dpp v229, v229, v229 quad_perm:[2,3,0,1] row_mask:0xf bank_mask:0xf
	v_add_f32_dpp v226, v226, v226 row_half_mirror row_mask:0xf bank_mask:0xf
	v_add_f32_dpp v227, v227, v227 row_half_mirror row_mask:0xf bank_mask:0xf
	v_add_f32_dpp v228, v228, v228 row_half_mirror row_mask:0xf bank_mask:0xf
	v_add_f32_dpp v229, v229, v229 row_half_mirror row_mask:0xf bank_mask:0xf
	v_add_f32_dpp v226, v226, v226 row_mirror row_mask:0xf bank_mask:0xf
	v_add_f32_dpp v227, v227, v227 row_mirror row_mask:0xf bank_mask:0xf
	v_add_f32_dpp v228, v228, v228 row_mirror row_mask:0xf bank_mask:0xf
	v_add_f32_dpp v229, v229, v229 row_mirror row_mask:0xf bank_mask:0xf
	s_waitcnt lgkmcnt(6)
	v_pk_fma_f32 v[170:171], v[226:227], v[218:219], v[230:231] op_sel_hi:[1,0,1] neg_lo:[1,0,0] neg_hi:[1,0,0]
	v_pk_fma_f32 v[172:173], v[226:227], v[218:219], v[232:233] op_sel:[0,1,0] neg_lo:[1,0,0] neg_hi:[1,0,0]
	v_pk_fma_f32 v[174:175], v[226:227], v[220:221], v[234:235] op_sel_hi:[1,0,1] neg_lo:[1,0,0] neg_hi:[1,0,0]
	v_pk_fma_f32 v[176:177], v[226:227], v[220:221], v[236:237] op_sel:[0,1,0] neg_lo:[1,0,0] neg_hi:[1,0,0]
	v_pk_fma_f32 v[246:247], v[226:227], v[224:225], v[228:229] op_sel_hi:[1,0,1] neg_lo:[1,0,0] neg_hi:[1,0,0]
	v_pk_fma_f32 v[246:247], v[222:223], v[224:225], v[246:247] op_sel:[0,1,0]
	ds_read_b128 v[194:197], v240 offset:50176
	ds_read_b64 v[200:201], v243 offset:32
	s_mov_b64 exec, s[60:61]
	ds_write_b64 v242, v[246:247] offset:17152
	s_mov_b64 exec, -1
	s_waitcnt lgkmcnt(6)
	v_pk_mul_f32 v[226:227], v[170:171], v[178:179] op_sel_hi:[1,0]
	v_pk_mul_f32 v[228:229], v[170:171], v[182:183] op_sel_hi:[1,0]
	v_pk_fma_f32 v[226:227], v[172:173], v[178:179], v[226:227] op_sel:[0,1,0]
	v_pk_fma_f32 v[228:229], v[172:173], v[182:183], v[228:229] op_sel:[0,1,0]
	v_pk_fma_f32 v[226:227], v[174:175], v[180:181], v[226:227] op_sel_hi:[1,0,1]
	v_pk_fma_f32 v[228:229], v[174:175], v[184:185], v[228:229] op_sel_hi:[1,0,1]
	v_pk_fma_f32 v[226:227], v[176:177], v[180:181], v[226:227] op_sel:[0,1,0]
	v_pk_fma_f32 v[228:229], v[176:177], v[184:185], v[228:229] op_sel:[0,1,0]
	ds_read_b128 v[202:205], v240 offset:34048
	ds_read_b128 v[206:209], v240 offset:1280
	s_waitcnt lgkmcnt(5)
; __device__ __forceinline__ void phase_rw_scan(KP P, const Ctx& c) {
;     ...
;             RW_LLOAD(A, 0);
; #pragma unroll 1
;             for (int tk = 0; tk < 64; tk += 2) {
;                 RW_LLOAD(B, tk + 1);
;                 RW_STEP(A, tk);
;                 RW_LLOAD(A, (tk + 2) & 63);
;                 RW_STEP(B, tk + 1);
;             }
	v_pk_mul_f32 v[230:231], v[170:171], v[186:187] op_sel_hi:[1,0]
	v_pk_mul_f32 v[232:233], v[172:173], v[186:187] op_sel:[0,1]
	v_pk_mul_f32 v[234:235], v[174:175], v[188:189] op_sel_hi:[1,0]
	v_pk_mul_f32 v[236:237], v[176:177], v[188:189] op_sel:[0,1]
	v_pk_fma_f32 v[230:231], v[198:199], v[190:191], v[230:231] op_sel_hi:[1,0,1]
	v_pk_fma_f32 v[232:233], v[198:199], v[190:191], v[232:233] op_sel:[0,1,0]
	v_pk_fma_f32 v[234:235], v[198:199], v[192:193], v[234:235] op_sel_hi:[1,0,1]
	v_pk_fma_f32 v[236:237], v[198:199], v[192:193], v[236:237] op_sel:[0,1,0]
	ds_read_b128 v[210:213], v240 offset:17664
	ds_read_b128 v[214:217], v241 offset:1280
	ds_read_b64 v[222:223], v242 offset:1280
	v_add_f32_dpp v226, v226, v226 quad_perm:[1,0,3,2] row_mask:0xf bank_mask:0xf
	v_add_f32_dpp v227, v227, v227 quad_perm:[1,0,3,2] row_mask:0xf bank_mask:0xf
	v_add_f32_dpp v228, v228, v228 quad_perm:[1,0,3,2] row_mask:0xf bank_mask:0xf
	v_add_f32_dpp v229, v229, v229 quad_perm:[1,0,3,2] row_mask:0xf bank_mask:0xf
	v_add_f32_dpp v226, v226, v226 quad_perm:[2,3,0,1] row_mask:0xf bank_mask:0xf
	v_add_f32_dpp v227, v227, v227 quad_perm:[2,3,0,1] row_mask:0xf bank_mask:0xf
	v_add_f32_dpp v228, v228, v228 quad_perm:[2,3,0,1] row_mask:0xf bank_mask:0xf
	v_add_f32_dpp v229, v229, v229 quad_perm:[2,3,0,1] row_mask:0xf bank_mask:0xf
	v_add_f32_dpp v226, v226, v226 row_half_mirror row_mask:0xf bank_mask:0xf
	v_add_f32_dpp v227, v227, v227 row_half_mirror row_mask:0xf bank_mask:0xf
	v_add_f32_dpp v228, v228, v228 row_half_mirror row_mask:0xf bank_mask:0xf
	v_add_f32_dpp v229, v229, v229 row_half_mirror row_mask:0xf bank_mask:0xf
	v_add_f32_dpp v226, v226, v226 row_mirror row_mask:0xf bank_mask:0xf
	v_add_f32_dpp v227, v227, v227 row_mirror row_mask:0xf bank_mask:0xf
	v_add_f32_dpp v228, v228, v228 row_mirror row_mask:0xf bank_mask:0xf
	v_add_f32_dpp v229, v229, v229 row_mirror row_mask:0xf bank_mask:0xf
	s_waitcnt lgkmcnt(6)
	v_pk_fma_f32 v[170:171], v[226:227], v[194:195], v[230:231] op_sel_hi:[1,0,1] neg_lo:[1,0,0] neg_hi:[1,0,0]
	v_pk_fma_f32 v[172:173], v[226:227], v[194:195], v[232:233] op_sel:[0,1,0] neg_lo:[1,0,0] neg_hi:[1,0,0]
	v_pk_fma_f32 v[174:175], v[226:227], v[196:197], v[234:235] op_sel_hi:[1,0,1] neg_lo:[1,0,0] neg_hi:[1,0,0]
	v_pk_fma_f32 v[176:177], v[226:227], v[196:197], v[236:237] op_sel:[0,1,0] neg_lo:[1,0,0] neg_hi:[1,0,0]
	v_pk_fma_f32 v[246:247], v[226:227], v[200:201], v[228:229] op_sel_hi:[1,0,1] neg_lo:[1,0,0] neg_hi:[1,0,0]
	v_pk_fma_f32 v[246:247], v[198:199], v[200:201], v[246:247] op_sel:[0,1,0]
	ds_read_b128 v[218:221], v240 offset:50432
	ds_read_b64 v[224:225], v243 offset:40
	s_mov_b64 exec, s[60:61]
	ds_write_b64 v242, v[246:247] offset:17408
	s_mov_b64 exec, -1
	s_waitcnt lgkmcnt(6)
	v_pk_mul_f32 v[226:227], v[170:171], v[202:203] op_sel_hi:[1,0]
	v_pk_mul_f32 v[228:229], v[170:171], v[206:207] op_sel_hi:[1,0]
	v_pk_fma_f32 v[226:227], v[172:173], v[202:203], v[226:227] op_sel:[0,1,0]
	v_pk_fma_f32 v[228:229], v[172:173], v[206:207], v[228:229] op_sel:[0,1,0]
	v_pk_fma_f32 v[226:227], v[174:175], v[204:205], v[226:227] op_sel_hi:[1,0,1]
	v_pk_fma_f32 v[228:229], v[174:175], v[208:209], v[228:229] op_sel_hi:[1,0,1]
	v_pk_fma_f32 v[226:227], v[176:177], v[204:205], v[226:227] op_sel:[0,1,0]
	v_pk_fma_f32 v[228:229], v[176:177], v[208:209], v[228:229] op_sel:[0,1,0]
	ds_read_b128 v[178:181], v240 offset:34304
	ds_read_b128 v[182:185], v240 offset:1536
	s_waitcnt lgkmcnt(5)
	v_pk_mul_f32 v[230:231], v[170:171], v[210:211] op_sel_hi:[1,0]
	v_pk_mul_f32 v[232:233], v[172:173], v[210:211] op_sel:[0,1]
	v_pk_mul_f32 v[234:235], v[174:175], v[212:213] op_sel_hi:[1,0]
	v_pk_mul_f32 v[236:237], v[176:177], v[212:213] op_sel:[0,1]
	v_pk_fma_f32 v[230:231], v[222:223], v[214:215], v[230:231] op_sel_hi:[1,0,1]
	v_pk_fma_f32 v[232:233], v[222:223], v[214:215], v[232:233] op_sel:[0,1,0]
	v_pk_fma_f32 v[234:235], v[222:223], v[216:217], v[234:235] op_sel_hi:[1,0,1]
	v_pk_fma_f32 v[236:237], v[222:223], v[216:217], v[236:237] op_sel:[0,1,0]
	ds_read_b128 v[186:189], v240 offset:17920
	ds_read_b128 v[190:193], v241 offset:1536
	ds_read_b64 v[198:199], v242 offset:1536
	v_add_f32_dpp v226, v226, v226 quad_perm:[1,0,3,2] row_mask:0xf bank_mask:0xf
	v_add_f32_dpp v227, v227, v227 quad_perm:[1,0,3,2] row_mask:0xf bank_mask:0xf
	v_add_f32_dpp v228, v228, v228 quad_perm:[1,0,3,2] row_mask:0xf bank_mask:0xf
	v_add_f32_dpp v229, v229, v229 quad_perm:[1,0,3,2] row_mask:0xf bank_mask:0xf
	v_add_f32_dpp v226, v226, v226 quad_perm:[2,3,0,1] row_mask:0xf bank_mask:0xf
	v_add_f32_dpp v227, v227, v227 quad_perm:[2,3,0,1] row_mask:0xf bank_mask:0xf
	v_add_f32_dpp v228, v228, v228 quad_perm:[2,3,0,1] row_mask:0xf bank_mask:0xf
	v_add_f32_dpp v229, v229, v229 quad_perm:[2,3,0,1] row_mask:0xf bank_mask:0xf
	v_add_f32_dpp v226, v226, v226 row_half_mirror row_mask:0xf bank_mask:0xf
	v_add_f32_dpp v227, v227, v227 row_half_mirror row_mask:0xf bank_mask:0xf
	v_add_f32_dpp v228, v228, v228 row_half_mirror row_mask:0xf bank_mask:0xf
	v_add_f32_dpp v229, v229, v229 row_half_mirror row_mask:0xf bank_mask:0xf
	v_add_f32_dpp v226, v226, v226 row_mirror row_mask:0xf bank_mask:0xf
	v_add_f32_dpp v227, v227, v227 row_mirror row_mask:0xf bank_mask:0xf
	v_add_f32_dpp v228, v228, v228 row_mirror row_mask:0xf bank_mask:0xf
	v_add_f32_dpp v229, v229, v229 row_mirror row_mask:0xf bank_mask:0xf
	s_waitcnt lgkmcnt(6)
; __device__ __forceinline__ void phase_rw_scan(KP P, const Ctx& c) {
;     ...
;             RW_LLOAD(A, 0);
; #pragma unroll 1
;             for (int tk = 0; tk < 64; tk += 2) {
;                 RW_LLOAD(B, tk + 1);
;                 RW_STEP(A, tk);
;                 RW_LLOAD(A, (tk + 2) & 63);
;                 RW_STEP(B, tk + 1);
;             }
	v_pk_fma_f32 v[170:171], v[226:227], v[218:219], v[230:231] op_sel_hi:[1,0,1] neg_lo:[1,0,0] neg_hi:[1,0,0]
	v_pk_fma_f32 v[172:173], v[226:227], v[218:219], v[232:233] op_sel:[0,1,0] neg_lo:[1,0,0] neg_hi:[1,0,0]
	v_pk_fma_f32 v[174:175], v[226:227], v[220:221], v[234:235] op_sel_hi:[1,0,1] neg_lo:[1,0,0] neg_hi:[1,0,0]
	v_pk_fma_f32 v[176:177], v[226:227], v[220:221], v[236:237] op_sel:[0,1,0] neg_lo:[1,0,0] neg_hi:[1,0,0]
	v_pk_fma_f32 v[246:247], v[226:227], v[224:225], v[228:229] op_sel_hi:[1,0,1] neg_lo:[1,0,0] neg_hi:[1,0,0]
	v_pk_fma_f32 v[246:247], v[222:223], v[224:225], v[246:247] op_sel:[0,1,0]
	ds_read_b128 v[194:197], v240 offset:50688
	ds_read_b64 v[200:201], v243 offset:48
	s_mov_b64 exec, s[60:61]
	ds_write_b64 v242, v[246:247] offset:17664
	s_mov_b64 exec, -1
	s_waitcnt lgkmcnt(6)
	v_pk_mul_f32 v[226:227], v[170:171], v[178:179] op_sel_hi:[1,0]
	v_pk_mul_f32 v[228:229], v[170:171], v[182:183] op_sel_hi:[1,0]
	v_pk_fma_f32 v[226:227], v[172:173], v[178:179], v[226:227] op_sel:[0,1,0]
	v_pk_fma_f32 v[228:229], v[172:173], v[182:183], v[228:229] op_sel:[0,1,0]
	v_pk_fma_f32 v[226:227], v[174:175], v[180:181], v[226:227] op_sel_hi:[1,0,1]
	v_pk_fma_f32 v[228:229], v[174:175], v[184:185], v[228:229] op_sel_hi:[1,0,1]
	v_pk_fma_f32 v[226:227], v[176:177], v[180:181], v[226:227] op_sel:[0,1,0]
	v_pk_fma_f32 v[228:229], v[176:177], v[184:185], v[228:229] op_sel:[0,1,0]
	ds_read_b128 v[202:205], v240 offset:34560
	ds_read_b128 v[206:209], v240 offset:1792
	s_waitcnt lgkmcnt(5)
	v_pk_mul_f32 v[230:231], v[170:171], v[186:187] op_sel_hi:[1,0]
	v_pk_mul_f32 v[232:233], v[172:173], v[186:187] op_sel:[0,1]
	v_pk_mul_f32 v[234:235], v[174:175], v[188:189] op_sel_hi:[1,0]
	v_pk_mul_f32 v[236:237], v[176:177], v[188:189] op_sel:[0,1]
	v_pk_fma_f32 v[230:231], v[198:199], v[190:191], v[230:231] op_sel_hi:[1,0,1]
	v_pk_fma_f32 v[232:233], v[198:199], v[190:191], v[232:233] op_sel:[0,1,0]
	v_pk_fma_f32 v[234:235], v[198:199], v[192:193], v[234:235] op_sel_hi:[1,0,1]
	v_pk_fma_f32 v[236:237], v[198:199], v[192:193], v[236:237] op_sel:[0,1,0]
	ds_read_b128 v[210:213], v240 offset:18176
	ds_read_b128 v[214:217], v241 offset:1792
	ds_read_b64 v[222:223], v242 offset:1792
	v_add_f32_dpp v226, v226, v226 quad_perm:[1,0,3,2] row_mask:0xf bank_mask:0xf
	v_add_f32_dpp v227, v227, v227 quad_perm:[1,0,3,2] row_mask:0xf bank_mask:0xf
	v_add_f32_dpp v228, v228, v228 quad_perm:[1,0,3,2] row_mask:0xf bank_mask:0xf
	v_add_f32_dpp v229, v229, v229 quad_perm:[1,0,3,2] row_mask:0xf bank_mask:0xf
	v_add_f32_dpp v226, v226, v226 quad_perm:[2,3,0,1] row_mask:0xf bank_mask:0xf
	v_add_f32_dpp v227, v227, v227 quad_perm:[2,3,0,1] row_mask:0xf bank_mask:0xf
	v_add_f32_dpp v228, v228, v228 quad_perm:[2,3,0,1] row_mask:0xf bank_mask:0xf
	v_add_f32_dpp v229, v229, v229 quad_perm:[2,3,0,1] row_mask:0xf bank_mask:0xf
	v_add_f32_dpp v226, v226, v226 row_half_mirror row_mask:0xf bank_mask:0xf
	v_add_f32_dpp v227, v227, v227 row_half_mirror row_mask:0xf bank_mask:0xf
	v_add_f32_dpp v228, v228, v228 row_half_mirror row_mask:0xf bank_mask:0xf
	v_add_f32_dpp v229, v229, v229 row_half_mirror row_mask:0xf bank_mask:0xf
	v_add_f32_dpp v226, v226, v226 row_mirror row_mask:0xf bank_mask:0xf
	v_add_f32_dpp v227, v227, v227 row_mirror row_mask:0xf bank_mask:0xf
	v_add_f32_dpp v228, v228, v228 row_mirror row_mask:0xf bank_mask:0xf
	v_add_f32_dpp v229, v229, v229 row_mirror row_mask:0xf bank_mask:0xf
	s_waitcnt lgkmcnt(6)
	v_pk_fma_f32 v[170:171], v[226:227], v[194:195], v[230:231] op_sel_hi:[1,0,1] neg_lo:[1,0,0] neg_hi:[1,0,0]
	v_pk_fma_f32 v[172:173], v[226:227], v[194:195], v[232:233] op_sel:[0,1,0] neg_lo:[1,0,0] neg_hi:[1,0,0]
	v_pk_fma_f32 v[174:175], v[226:227], v[196:197], v[234:235] op_sel_hi:[1,0,1] neg_lo:[1,0,0] neg_hi:[1,0,0]
	v_pk_fma_f32 v[176:177], v[226:227], v[196:197], v[236:237] op_sel:[0,1,0] neg_lo:[1,0,0] neg_hi:[1,0,0]
	v_pk_fma_f32 v[246:247], v[226:227], v[200:201], v[228:229] op_sel_hi:[1,0,1] neg_lo:[1,0,0] neg_hi:[1,0,0]
	v_pk_fma_f32 v[246:247], v[198:199], v[200:201], v[246:247] op_sel:[0,1,0]
	ds_read_b128 v[218:221], v240 offset:50944
	ds_read_b64 v[224:225], v243 offset:56
	s_mov_b64 exec, s[60:61]
	ds_write_b64 v242, v[246:247] offset:17920
	s_mov_b64 exec, -1
	s_waitcnt lgkmcnt(6)
; __device__ __forceinline__ void phase_rw_scan(KP P, const Ctx& c) {
;     ...
;             RW_LLOAD(A, 0);
; #pragma unroll 1
;             for (int tk = 0; tk < 64; tk += 2) {
;                 RW_LLOAD(B, tk + 1);
;                 RW_STEP(A, tk);
;                 RW_LLOAD(A, (tk + 2) & 63);
;                 RW_STEP(B, tk + 1);
;             }
	v_pk_mul_f32 v[226:227], v[170:171], v[202:203] op_sel_hi:[1,0]
	v_pk_mul_f32 v[228:229], v[170:171], v[206:207] op_sel_hi:[1,0]
	v_pk_fma_f32 v[226:227], v[172:173], v[202:203], v[226:227] op_sel:[0,1,0]
	v_pk_fma_f32 v[228:229], v[172:173], v[206:207], v[228:229] op_sel:[0,1,0]
	v_pk_fma_f32 v[226:227], v[174:175], v[204:205], v[226:227] op_sel_hi:[1,0,1]
	v_pk_fma_f32 v[228:229], v[174:175], v[208:209], v[228:229] op_sel_hi:[1,0,1]
	v_pk_fma_f32 v[226:227], v[176:177], v[204:205], v[226:227] op_sel:[0,1,0]
	v_pk_fma_f32 v[228:229], v[176:177], v[208:209], v[228:229] op_sel:[0,1,0]
	ds_read_b128 v[178:181], v240 offset:34816
	ds_read_b128 v[182:185], v240 offset:2048
	s_waitcnt lgkmcnt(5)
	v_pk_mul_f32 v[230:231], v[170:171], v[210:211] op_sel_hi:[1,0]
	v_pk_mul_f32 v[232:233], v[172:173], v[210:211] op_sel:[0,1]
	v_pk_mul_f32 v[234:235], v[174:175], v[212:213] op_sel_hi:[1,0]
	v_pk_mul_f32 v[236:237], v[176:177], v[212:213] op_sel:[0,1]
	v_pk_fma_f32 v[230:231], v[222:223], v[214:215], v[230:231] op_sel_hi:[1,0,1]
	v_pk_fma_f32 v[232:233], v[222:223], v[214:215], v[232:233] op_sel:[0,1,0]
	v_pk_fma_f32 v[234:235], v[222:223], v[216:217], v[234:235] op_sel_hi:[1,0,1]
	v_pk_fma_f32 v[236:237], v[222:223], v[216:217], v[236:237] op_sel:[0,1,0]
	ds_read_b128 v[186:189], v240 offset:18432
	ds_read_b128 v[190:193], v241 offset:2048
	ds_read_b64 v[198:199], v242 offset:2048
	v_add_f32_dpp v226, v226, v226 quad_perm:[1,0,3,2] row_mask:0xf bank_mask:0xf
	v_add_f32_dpp v227, v227, v227 quad_perm:[1,0,3,2] row_mask:0xf bank_mask:0xf
	v_add_f32_dpp v228, v228, v228 quad_perm:[1,0,3,2] row_mask:0xf bank_mask:0xf
	v_add_f32_dpp v229, v229, v229 quad_perm:[1,0,3,2] row_mask:0xf bank_mask:0xf
	v_add_f32_dpp v226, v226, v226 quad_perm:[2,3,0,1] row_mask:0xf bank_mask:0xf
	v_add_f32_dpp v227, v227, v227 quad_perm:[2,3,0,1] row_mask:0xf bank_mask:0xf
	v_add_f32_dpp v228, v228, v228 quad_perm:[2,3,0,1] row_mask:0xf bank_mask:0xf
	v_add_f32_dpp v229, v229, v229 quad_perm:[2,3,0,1] row_mask:0xf bank_mask:0xf
	v_add_f32_dpp v226, v226, v226 row_half_mirror row_mask:0xf bank_mask:0xf
	v_add_f32_dpp v227, v227, v227 row_half_mirror row_mask:0xf bank_mask:0xf
	v_add_f32_dpp v228, v228, v228 row_half_mirror row_mask:0xf bank_mask:0xf
	v_add_f32_dpp v229, v229, v229 row_half_mirror row_mask:0xf bank_mask:0xf
	v_add_f32_dpp v226, v226, v226 row_mirror row_mask:0xf bank_mask:0xf
	v_add_f32_dpp v227, v227, v227 row_mirror row_mask:0xf bank_mask:0xf
	v_add_f32_dpp v228, v228, v228 row_mirror row_mask:0xf bank_mask:0xf
	v_add_f32_dpp v229, v229, v229 row_mirror row_mask:0xf bank_mask:0xf
	s_waitcnt lgkmcnt(6)
	v_pk_fma_f32 v[170:171], v[226:227], v[218:219], v[230:231] op_sel_hi:[1,0,1] neg_lo:[1,0,0] neg_hi:[1,0,0]
	v_pk_fma_f32 v[172:173], v[226:227], v[218:219], v[232:233] op_sel:[0,1,0] neg_lo:[1,0,0] neg_hi:[1,0,0]
	v_pk_fma_f32 v[174:175], v[226:227], v[220:221], v[234:235] op_sel_hi:[1,0,1] neg_lo:[1,0,0] neg_hi:[1,0,0]
	v_pk_fma_f32 v[176:177], v[226:227], v[220:221], v[236:237] op_sel:[0,1,0] neg_lo:[1,0,0] neg_hi:[1,0,0]
	v_pk_fma_f32 v[246:247], v[226:227], v[224:225], v[228:229] op_sel_hi:[1,0,1] neg_lo:[1,0,0] neg_hi:[1,0,0]
	v_pk_fma_f32 v[246:247], v[222:223], v[224:225], v[246:247] op_sel:[0,1,0]
	ds_read_b128 v[194:197], v240 offset:51200
	ds_read_b64 v[200:201], v243 offset:64
	s_mov_b64 exec, s[60:61]
	ds_write_b64 v242, v[246:247] offset:18176
	s_mov_b64 exec, -1
	v_add_u32_e32 v240, 0x800, v240
	v_add_u32_e32 v241, 0x800, v241
	v_add_u32_e32 v242, 0x800, v242
	v_add_u32_e32 v243, 0x40, v243
	s_add_i32 s62, s62, 1
	s_cmp_lt_u32 s62, 8
	s_cbranch_scc1 .Lrw_loop
	s_branch .LBB0_1754

; __global__ void __launch_bounds__(512, 2) hybrid_fwd(Params Pkernarg) {
;     extern __shared__ __attribute__((aligned(16))) unsigned char lds_raw[];
	.amdhsa_kernel _Z10hybrid_fwd6Params
		.amdhsa_group_segment_fixed_size 0
		.amdhsa_private_segment_fixed_size 0
		.amdhsa_kernarg_size 568
		.amdhsa_user_sgpr_count 2
		.amdhsa_user_sgpr_dispatch_ptr 0
		.amdhsa_user_sgpr_queue_ptr 0
		.amdhsa_user_sgpr_kernarg_segment_ptr 1
		.amdhsa_user_sgpr_dispatch_id 0
		.amdhsa_user_sgpr_kernarg_preload_length 0
		.amdhsa_user_sgpr_kernarg_preload_offset 0
		.amdhsa_user_sgpr_private_segment_size 0
		.amdhsa_uses_dynamic_stack 0
		.amdhsa_enable_private_segment 0
		.amdhsa_system_sgpr_workgroup_id_x 1
		.amdhsa_system_sgpr_workgroup_id_y 0
		.amdhsa_system_sgpr_workgroup_id_z 0
		.amdhsa_system_sgpr_workgroup_info 0
		.amdhsa_system_vgpr_workitem_id 0
		.amdhsa_next_free_vgpr 248
		.amdhsa_next_free_sgpr 98
		.amdhsa_accum_offset 248
		.amdhsa_reserve_vcc 1
		.amdhsa_float_round_mode_32 0
		.amdhsa_float_round_mode_16_64 0
		.amdhsa_float_denorm_mode_32 3
		.amdhsa_float_denorm_mode_16_64 3
		.amdhsa_dx10_clamp 1
		.amdhsa_ieee_mode 1
		.amdhsa_fp16_overflow 0
		.amdhsa_tg_split 0
		.amdhsa_exception_fp_ieee_invalid_op 0
		.amdhsa_exception_fp_denorm_src 0
		.amdhsa_exception_fp_ieee_div_zero 0
		.amdhsa_exception_fp_ieee_overflow 0
		.amdhsa_exception_fp_ieee_underflow 0
		.amdhsa_exception_fp_ieee_inexact 0
		.amdhsa_exception_int_div_zero 0
	.end_amdhsa_kernel

; __global__ void __launch_bounds__(512, 2) hybrid_fwd(Params Pkernarg) {
;     extern __shared__ __attribute__((aligned(16))) unsigned char lds_raw[];
amdhsa.kernels:
  - .agpr_count:     0
    .args:
      - .offset:         0
        .size:           312
        .value_kind:     by_value
      - .offset:         312
        .size:           4
        .value_kind:     hidden_block_count_x
      - .offset:         316
        .size:           4
        .value_kind:     hidden_block_count_y
      - .offset:         320
        .size:           4
        .value_kind:     hidden_block_count_z
      - .offset:         324
        .size:           2
        .value_kind:     hidden_group_size_x
      - .offset:         326
        .size:           2
        .value_kind:     hidden_group_size_y
      - .offset:         328
        .size:           2
        .value_kind:     hidden_group_size_z
      - .offset:         330
        .size:           2
        .value_kind:     hidden_remainder_x
      - .offset:         332
        .size:           2
        .value_kind:     hidden_remainder_y
      - .offset:         334
        .size:           2
        .value_kind:     hidden_remainder_z
      - .offset:         352
        .size:           8
        .value_kind:     hidden_global_offset_x
      - .offset:         360
        .size:           8
        .value_kind:     hidden_global_offset_y
      - .offset:         368
        .size:           8
        .value_kind:     hidden_global_offset_z
      - .offset:         376
        .size:           2
        .value_kind:     hidden_grid_dims
      - .offset:         432
        .size:           4
        .value_kind:     hidden_dynamic_lds_size
    .group_segment_fixed_size: 0
    .kernarg_segment_align: 8
    .kernarg_segment_size: 568
    .language:       OpenCL C
    .language_version:
      - 2
      - 0
    .max_flat_workgroup_size: 512
    .name:           _Z10hybrid_fwd6Params
    .private_segment_fixed_size: 0
    .sgpr_count:     104
    .sgpr_spill_count: 117
    .symbol:         _Z10hybrid_fwd6Params.kd
    .uniform_work_group_size: 1
    .uses_dynamic_stack: false
    .vgpr_count:     248
    .vgpr_spill_count: 0
    .wavefront_size: 64
